# sum-check attention loop moved to an 8-byte-aligned head (+4 B pad before, +4 B after)
# baseline (speedup 1.0000x reference)
; #define LAS __attribute__((address_space(3)))
; #define DMAT(kt, so) do { const unsigned rb_ = (unsigned)ROWBASE(kt); _Pragma("unroll") for (int r = 0; r < 3; ++r) if (wid + 8 * r < 22) \
;         __builtin_amdgcn_global_load_lds((const unsigned*)(dsrc[r] + (size_t)rb_ * dmul[r]), (LAS unsigned*)(lds + (so) + dlds[r]), 16, 0, 0); } while (0)
; __device__ __forceinline__ void attn_unit2(LAS unsigned char* lds, const bf16_t* __restrict__ Q, const bf16_t* __restrict__ KN, const bf16_t* __restrict__ KPE, ...
;     ...
;         f32x16 sa0 = {}, sa1 = {}, sb0 = {}, sb1 = {};
;         const LAS unsigned char* ka = lds + sc + ka_off;
; #pragma unroll
;         for (int ds = 0; ds < 6; ++ds) {
;             const bf16x8 k0 = *(const LAS bf16x8*)(ka + ds * 32);
;             const bf16x8 k1 = *(const LAS bf16x8*)(ka + 32 * KROW + ds * 32);
;             sa0 = __builtin_amdgcn_mfma_f32_32x32x16_bf16(k0, qa[ds], sa0, 0, 0, 0);
;             sa1 = __builtin_amdgcn_mfma_f32_32x32x16_bf16(k1, qa[ds], sa1, 0, 0, 0);
;             sb0 = __builtin_amdgcn_mfma_f32_32x32x16_bf16(k0, qb[ds], sb0, 0, 0, 0);
;             sb1 = __builtin_amdgcn_mfma_f32_32x32x16_bf16(k1, qb[ds], sb1, 0, 0, 0);
;         }
;         __builtin_amdgcn_sched_barrier(0);
;         if (t + 2 < ntiles) DMAT(t + 2, snn);
;         u32x4 pa[4], pb[4];
.Lat_noprio:
	v_mov_b32_e32 v96, 0
	v_mov_b32_e32 v97, 0
	v_mov_b32_e32 v98, 0
	v_mov_b32_e32 v99, 0
	v_mov_b32_e32 v100, 0
	v_mov_b32_e32 v101, 0
	v_mov_b32_e32 v102, 0
	v_mov_b32_e32 v103, 0
	v_mov_b32_e32 v112, 0
	v_mov_b32_e32 v113, 0
	v_mov_b32_e32 v114, 0
	v_mov_b32_e32 v115, 0
	v_mov_b32_e32 v116, 0
	v_mov_b32_e32 v117, 0
	v_mov_b32_e32 v118, 0
	v_mov_b32_e32 v119, 0
	v_sub_u32_e32 v228, 1, v192
	v_mul_u32_u24_e32 v228, 0xffff, v228
	v_and_b32_e32 v240, 0x3f80, v228
	v_mov_b32_e32 v241, 0
	v_mov_b32_e32 v242, 0
	v_mov_b32_e32 v243, 0
	v_mov_b32_e32 v245, 0
	v_mov_b32_e32 v246, 0
	v_mov_b32_e32 v247, 0
	v_mov_b32_e32 v249, 0
	v_mov_b32_e32 v250, 0
	v_mov_b32_e32 v251, 0
	v_add3_u32 v224, s34, v183, v128
	ds_read_b128 v[212:215], v224 offset:0
	ds_read_b128 v[216:219], v224 offset:32
	ds_read_b128 v[220:223], v224 offset:64
	s_waitcnt lgkmcnt(2)
	v_mfma_f32_32x32x16_bf16 v[64:79], v[212:215], v[130:133], 0
	v_mfma_f32_32x32x16_bf16 v[80:95], v[212:215], v[138:141], 0
	ds_read_b128 v[212:215], v224 offset:96
	s_waitcnt lgkmcnt(2)
	v_mfma_f32_32x32x16_bf16 v[64:79], v[216:219], v[134:137], v[64:79]
	v_mfma_f32_32x32x16_bf16 v[80:95], v[216:219], v[142:145], v[80:95]
	ds_read_b128 v[216:219], v224 offset:128
	s_waitcnt lgkmcnt(2)
	v_mfma_f32_32x32x16_bf16 v[64:79], v[220:223], v[146:149], v[64:79]
	v_mfma_f32_32x32x16_bf16 v[80:95], v[220:223], v[154:157], v[80:95]
	ds_read_b128 v[220:223], v224 offset:160
	s_waitcnt lgkmcnt(2)
	v_mfma_f32_32x32x16_bf16 v[64:79], v[212:215], v[150:153], v[64:79]
	v_mfma_f32_32x32x16_bf16 v[80:95], v[212:215], v[158:161], v[80:95]
	s_waitcnt lgkmcnt(1)
	v_mfma_f32_32x32x16_bf16 v[64:79], v[216:219], v[162:165], v[64:79]
	v_mfma_f32_32x32x16_bf16 v[80:95], v[216:219], v[170:173], v[80:95]
	s_waitcnt lgkmcnt(0)
	v_mfma_f32_32x32x16_bf16 v[64:79], v[220:223], v[166:169], v[64:79]
	v_mfma_f32_32x32x16_bf16 v[80:95], v[220:223], v[174:177], v[80:95]
	s_nop 15
	s_nop 3
	v_max3_f32 v226, v64, v65, v66
	v_max3_f32 v227, v67, v68, v69
	v_max3_f32 v226, v226, v70, v71
	v_max3_f32 v227, v227, v72, v73
	v_max3_f32 v226, v226, v74, v75
	v_max3_f32 v227, v227, v76, v77
	v_max3_f32 v226, v226, v78, v79
	v_max_f32_e32 v226, v226, v227
	v_mov_b32_e32 v227, v226
	s_nop 1
	v_permlane32_swap_b32_e32 v226, v227
	v_max_f32_e32 v226, v226, v227
	v_cvt_pk_bf16_f32 v227, v226, v226
	v_and_b32_e32 v194, 0xffff0000, v227
	v_xor_b32_e32 v227, 0x80000000, v194
	v_lshrrev_b32_e32 v227, 16, v227
	v_and_b32_e32 v244, v228, v227
	v_max3_f32 v236, v80, v81, v82
	v_max3_f32 v237, v83, v84, v85
	v_max3_f32 v236, v236, v86, v87
	v_max3_f32 v237, v237, v88, v89
	v_max3_f32 v236, v236, v90, v91
	v_max3_f32 v237, v237, v92, v93
	v_max3_f32 v236, v236, v94, v95
	v_max_f32_e32 v236, v236, v237
	v_mov_b32_e32 v237, v236
	s_nop 1
	v_permlane32_swap_b32_e32 v236, v237
	v_max_f32_e32 v236, v236, v237
	v_cvt_pk_bf16_f32 v237, v236, v236
	v_and_b32_e32 v195, 0xffff0000, v237
	v_xor_b32_e32 v237, 0x80000000, v195
	v_lshrrev_b32_e32 v237, 16, v237
	v_and_b32_e32 v248, v228, v237
	s_nop 3
	v_mfma_f32_32x32x16_bf16 v[64:79], v[240:243], v[244:247], v[64:79]
	v_mfma_f32_32x32x16_bf16 v[80:95], v[240:243], v[248:251], v[80:95]
	v_add3_u32 v225, s34, v187, v128
	ds_read_b128 v[196:199], v225 offset:13376
	ds_read_b128 v[200:203], v225 offset:17984
	ds_read_b128 v[204:207], v225 offset:13408
	ds_read_b128 v[208:211], v225 offset:18016
	s_nop 7
	s_nop 3
	s_nop 0
